# accumulator zeroing with v_mov_b64 (64 instead of 128 moves per unit) on top of previous version
# speedup vs baseline: 1.0093x; 1.0093x over previous
.LBB0_367:
	s_ashr_i32 s55, s54, 31
	s_lshl_b64 s[2:3], s[54:55], 19
	s_add_u32 s58, s4, s2
	s_addc_u32 s59, s5, s3
	s_and_b64 s[2:3], s[56:57], exec
	s_cselect_b32 s2, s59, s7
	s_cselect_b32 s3, s58, s6
	s_ashr_i32 s53, s52, 31
	s_lshl_b64 s[10:11], s[52:53], 19
	s_add_u32 s60, s15, s10
	s_addc_u32 s61, s78, s11
	s_and_b64 s[10:11], s[56:57], exec
	s_cselect_b32 s12, s61, s9
	s_cselect_b32 s13, s60, s8
	s_add_u32 s6, s6, 0x40080
	s_addc_u32 s7, s7, 0
	s_add_u32 s24, s8, 0x100
	v_mov_b64_e32 v[2:3], 0
	s_addc_u32 s25, s9, 0
	s_mov_b32 s26, -2
	v_mov_b64_e32 v[4:5], 0
	v_mov_b64_e32 v[6:7], 0
	v_mov_b64_e32 v[8:9], 0
	v_mov_b64_e32 v[18:19], 0
	v_mov_b64_e32 v[20:21], 0
	v_mov_b64_e32 v[22:23], 0
	v_mov_b64_e32 v[24:25], 0
	v_mov_b64_e32 v[34:35], 0
	v_mov_b64_e32 v[36:37], 0
	v_mov_b64_e32 v[38:39], 0
	v_mov_b64_e32 v[40:41], 0
	v_mov_b64_e32 v[50:51], 0
	v_mov_b64_e32 v[52:53], 0
	v_mov_b64_e32 v[54:55], 0
	v_mov_b64_e32 v[56:57], 0
	v_mov_b64_e32 v[10:11], 0
	v_mov_b64_e32 v[12:13], 0
	v_mov_b64_e32 v[14:15], 0
	v_mov_b64_e32 v[16:17], 0
	v_mov_b64_e32 v[26:27], 0
	v_mov_b64_e32 v[28:29], 0
	s_waitcnt vmcnt(0)
	v_mov_b64_e32 v[30:31], 0
	v_mov_b64_e32 v[32:33], 0
	v_mov_b64_e32 v[42:43], 0
	v_mov_b64_e32 v[44:45], 0
	v_mov_b64_e32 v[46:47], 0
	v_mov_b64_e32 v[48:49], 0
	v_mov_b64_e32 v[58:59], 0
	v_mov_b64_e32 v[60:61], 0
	v_mov_b64_e32 v[62:63], 0
	v_mov_b64_e32 v[64:65], 0
	v_mov_b64_e32 v[66:67], 0
	v_mov_b64_e32 v[68:69], 0
	v_mov_b64_e32 v[70:71], 0
	v_mov_b64_e32 v[72:73], 0
	v_mov_b64_e32 v[82:83], 0
	v_mov_b64_e32 v[84:85], 0
	v_mov_b64_e32 v[86:87], 0
	v_mov_b64_e32 v[88:89], 0
	v_mov_b64_e32 v[98:99], 0
	v_mov_b64_e32 v[100:101], 0
	v_mov_b64_e32 v[102:103], 0
	v_mov_b64_e32 v[104:105], 0
	v_mov_b64_e32 v[118:119], 0
	v_mov_b64_e32 v[120:121], 0
	v_mov_b64_e32 v[122:123], 0
	v_mov_b64_e32 v[124:125], 0
	v_mov_b64_e32 v[74:75], 0
	v_mov_b64_e32 v[76:77], 0
	v_mov_b64_e32 v[78:79], 0
	v_mov_b64_e32 v[80:81], 0
	v_mov_b64_e32 v[90:91], 0
	v_mov_b64_e32 v[92:93], 0
	v_mov_b64_e32 v[94:95], 0
	v_mov_b64_e32 v[96:97], 0
	v_mov_b64_e32 v[106:107], 0
	v_mov_b64_e32 v[108:109], 0
	v_mov_b64_e32 v[110:111], 0
	v_mov_b64_e32 v[112:113], 0
	v_mov_b64_e32 v[126:127], 0
	v_mov_b64_e32 v[128:129], 0
	v_mov_b64_e32 v[130:131], 0
	v_mov_b64_e32 v[132:133], 0
.LBB0_368:
	ds_read_b128 v[114:117], v197
	ds_read_b128 v[134:137], v197 offset:1024
	ds_read_b128 v[138:141], v197 offset:2048
	ds_read_b128 v[142:145], v197 offset:3072
	ds_read_b128 v[146:149], v198
	ds_read_b128 v[150:153], v198 offset:1024
	ds_read_b128 v[154:157], v198 offset:2048
	ds_read_b128 v[158:161], v198 offset:3072
	s_add_u32 s0, s6, 0xfffc0080
	s_addc_u32 s8, s7, -1
	s_cmp_eq_u32 s26, 12
	s_cselect_b32 s11, s2, s8
	s_cselect_b32 s10, s3, s0
	s_cselect_b32 s9, s12, s25
	s_cselect_b32 s8, s13, s24
	v_lshl_add_u64 v[230:231], s[6:7], 0, v[180:181]
	s_add_i32 m0, s31, 0xc000
	ds_read_b128 v[184:187], v199
	ds_read_b128 v[188:191], v199 offset:1024
	ds_read_b128 v[206:209], v199 offset:2048
	ds_read_b128 v[210:213], v199 offset:3072
	ds_read_b128 v[214:217], v199 offset:4096
	ds_read_b128 v[218:221], v199 offset:5120
	ds_read_b128 v[222:225], v199 offset:6144
	ds_read_b128 v[226:229], v199 offset:7168
	global_load_lds_dwordx4 v[230:231], off
	v_lshl_add_u64 v[230:231], s[6:7], 0, v[182:183]
	s_add_i32 m0, s31, 0xe000
	s_nop 0
	global_load_lds_dwordx4 v[230:231], off
	s_waitcnt vmcnt(8)
	s_waitcnt lgkmcnt(0)
	s_barrier
	s_setprio 1
	s_waitcnt lgkmcnt(0)
	v_mfma_f32_16x16x32_bf16 v[130:133], v[114:117], v[184:187], v[130:133]
	v_mfma_f32_16x16x32_bf16 v[126:129], v[138:141], v[184:187], v[126:129]
	v_mfma_f32_16x16x32_bf16 v[110:113], v[114:117], v[206:209], v[110:113]
	v_mfma_f32_16x16x32_bf16 v[106:109], v[138:141], v[206:209], v[106:109]
	v_mfma_f32_16x16x32_bf16 v[94:97], v[114:117], v[214:217], v[94:97]
	v_mfma_f32_16x16x32_bf16 v[90:93], v[138:141], v[214:217], v[90:93]
	v_mfma_f32_16x16x32_bf16 v[78:81], v[114:117], v[222:225], v[78:81]
	v_mfma_f32_16x16x32_bf16 v[74:77], v[138:141], v[222:225], v[74:77]
	v_mfma_f32_16x16x32_bf16 v[130:133], v[134:137], v[188:191], v[130:133]
	v_mfma_f32_16x16x32_bf16 v[126:129], v[142:145], v[188:191], v[126:129]
	v_mfma_f32_16x16x32_bf16 v[110:113], v[134:137], v[210:213], v[110:113]
	v_mfma_f32_16x16x32_bf16 v[106:109], v[142:145], v[210:213], v[106:109]
	v_mfma_f32_16x16x32_bf16 v[94:97], v[134:137], v[218:221], v[94:97]
	v_mfma_f32_16x16x32_bf16 v[90:93], v[142:145], v[218:221], v[90:93]
	v_mfma_f32_16x16x32_bf16 v[78:81], v[134:137], v[226:229], v[78:81]
	v_mfma_f32_16x16x32_bf16 v[74:77], v[142:145], v[226:229], v[74:77]
	s_setprio 0
	s_setprio 1
	v_mfma_f32_16x16x32_bf16 v[122:125], v[146:149], v[184:187], v[122:125]
	v_mfma_f32_16x16x32_bf16 v[118:121], v[154:157], v[184:187], v[118:121]
	v_mfma_f32_16x16x32_bf16 v[102:105], v[146:149], v[206:209], v[102:105]
	v_mfma_f32_16x16x32_bf16 v[98:101], v[154:157], v[206:209], v[98:101]
	v_mfma_f32_16x16x32_bf16 v[86:89], v[146:149], v[214:217], v[86:89]
	v_mfma_f32_16x16x32_bf16 v[82:85], v[154:157], v[214:217], v[82:85]
	v_mfma_f32_16x16x32_bf16 v[70:73], v[146:149], v[222:225], v[70:73]
	v_mfma_f32_16x16x32_bf16 v[66:69], v[154:157], v[222:225], v[66:69]
	v_mfma_f32_16x16x32_bf16 v[122:125], v[150:153], v[188:191], v[122:125]
	v_mfma_f32_16x16x32_bf16 v[118:121], v[158:161], v[188:191], v[118:121]
	v_mfma_f32_16x16x32_bf16 v[102:105], v[150:153], v[210:213], v[102:105]
	v_mfma_f32_16x16x32_bf16 v[98:101], v[158:161], v[210:213], v[98:101]
	v_mfma_f32_16x16x32_bf16 v[86:89], v[150:153], v[218:221], v[86:89]
	v_mfma_f32_16x16x32_bf16 v[82:85], v[158:161], v[218:221], v[82:85]
	v_mfma_f32_16x16x32_bf16 v[70:73], v[150:153], v[226:229], v[70:73]
	v_mfma_f32_16x16x32_bf16 v[66:69], v[158:161], v[226:229], v[66:69]
	s_setprio 0
	s_barrier
	s_add_i32 s0, s89, s79
	v_lshl_add_u64 v[230:231], s[8:9], 0, v[164:165]
	s_mov_b32 m0, s0
	ds_read_b128 v[184:187], v199 offset:16384
	ds_read_b128 v[188:191], v199 offset:17408
	ds_read_b128 v[206:209], v199 offset:18432
	ds_read_b128 v[210:213], v199 offset:19456
	ds_read_b128 v[214:217], v199 offset:20480
	ds_read_b128 v[218:221], v199 offset:21504
	ds_read_b128 v[222:225], v199 offset:22528
	ds_read_b128 v[226:229], v199 offset:23552
	global_load_lds_dwordx4 v[230:231], off
	s_add_i32 m0, s0, 0x2000
	s_add_u32 s62, s8, 0x40000
	v_lshl_add_u64 v[232:233], s[8:9], 0, v[168:169]
	s_addc_u32 s63, s9, 0
	s_add_i32 s0, s90, s79
	global_load_lds_dwordx4 v[232:233], off
	v_lshl_add_u64 v[234:235], s[62:63], 0, v[164:165]
	s_mov_b32 m0, s0
	v_lshl_add_u64 v[236:237], s[10:11], 0, v[166:167]
	global_load_lds_dwordx4 v[234:235], off
	v_lshl_add_u64 v[234:235], s[62:63], 0, v[168:169]
	s_add_i32 m0, s0, 0x2000
	s_nop 0
	global_load_lds_dwordx4 v[234:235], off
	v_lshl_add_u64 v[234:235], s[10:11], 0, v[162:163]
	s_mov_b32 m0, s31
	s_nop 0
	global_load_lds_dwordx4 v[234:235], off
	s_mov_b32 m0, s80
	s_nop 0
	global_load_lds_dwordx4 v[236:237], off
	s_waitcnt vmcnt(8)
	s_waitcnt lgkmcnt(0)
	s_barrier
	s_setprio 1
	s_waitcnt lgkmcnt(0)
	v_mfma_f32_16x16x32_bf16 v[62:65], v[114:117], v[184:187], v[62:65]
	v_mfma_f32_16x16x32_bf16 v[58:61], v[138:141], v[184:187], v[58:61]
	v_mfma_f32_16x16x32_bf16 v[46:49], v[114:117], v[206:209], v[46:49]
	v_mfma_f32_16x16x32_bf16 v[42:45], v[138:141], v[206:209], v[42:45]
	v_mfma_f32_16x16x32_bf16 v[30:33], v[114:117], v[214:217], v[30:33]
	v_mfma_f32_16x16x32_bf16 v[26:29], v[138:141], v[214:217], v[26:29]
	v_mfma_f32_16x16x32_bf16 v[14:17], v[114:117], v[222:225], v[14:17]
	v_mfma_f32_16x16x32_bf16 v[10:13], v[138:141], v[222:225], v[10:13]
	v_mfma_f32_16x16x32_bf16 v[62:65], v[134:137], v[188:191], v[62:65]
	v_mfma_f32_16x16x32_bf16 v[58:61], v[142:145], v[188:191], v[58:61]
	v_mfma_f32_16x16x32_bf16 v[46:49], v[134:137], v[210:213], v[46:49]
	v_mfma_f32_16x16x32_bf16 v[42:45], v[142:145], v[210:213], v[42:45]
	v_mfma_f32_16x16x32_bf16 v[30:33], v[134:137], v[218:221], v[30:33]
	v_mfma_f32_16x16x32_bf16 v[26:29], v[142:145], v[218:221], v[26:29]
	v_mfma_f32_16x16x32_bf16 v[14:17], v[134:137], v[226:229], v[14:17]
	v_mfma_f32_16x16x32_bf16 v[10:13], v[142:145], v[226:229], v[10:13]
	s_setprio 0
	s_setprio 1
	v_mfma_f32_16x16x32_bf16 v[54:57], v[146:149], v[184:187], v[54:57]
	v_mfma_f32_16x16x32_bf16 v[50:53], v[154:157], v[184:187], v[50:53]
	v_mfma_f32_16x16x32_bf16 v[38:41], v[146:149], v[206:209], v[38:41]
	v_mfma_f32_16x16x32_bf16 v[34:37], v[154:157], v[206:209], v[34:37]
	v_mfma_f32_16x16x32_bf16 v[22:25], v[146:149], v[214:217], v[22:25]
	v_mfma_f32_16x16x32_bf16 v[18:21], v[154:157], v[214:217], v[18:21]
	v_mfma_f32_16x16x32_bf16 v[6:9], v[146:149], v[222:225], v[6:9]
	v_mfma_f32_16x16x32_bf16 v[2:5], v[154:157], v[222:225], v[2:5]
	v_mfma_f32_16x16x32_bf16 v[54:57], v[150:153], v[188:191], v[54:57]
	v_mfma_f32_16x16x32_bf16 v[50:53], v[158:161], v[188:191], v[50:53]
	v_mfma_f32_16x16x32_bf16 v[38:41], v[150:153], v[210:213], v[38:41]
	v_mfma_f32_16x16x32_bf16 v[34:37], v[158:161], v[210:213], v[34:37]
	v_mfma_f32_16x16x32_bf16 v[22:25], v[150:153], v[218:221], v[22:25]
	v_mfma_f32_16x16x32_bf16 v[18:21], v[158:161], v[218:221], v[18:21]
	v_mfma_f32_16x16x32_bf16 v[6:9], v[150:153], v[226:229], v[6:9]
	v_mfma_f32_16x16x32_bf16 v[2:5], v[158:161], v[226:229], v[2:5]
	s_setprio 0
	s_barrier
	s_add_i32 s0, 0, 0x18000
	s_add_i32 s27, 0, 0x1c000
	v_add_u32_e32 v142, s0, v173
	v_add_u32_e32 v158, s27, v173
	ds_read_b128 v[114:117], v142
	ds_read_b128 v[134:137], v142 offset:1024
	ds_read_b128 v[138:141], v142 offset:2048
	ds_read_b128 v[142:145], v142 offset:3072
	ds_read_b128 v[146:149], v158
	ds_read_b128 v[150:153], v158 offset:1024
	ds_read_b128 v[154:157], v158 offset:2048
	ds_read_b128 v[158:161], v158 offset:3072
	s_add_u32 s10, s10, 0x40000
	s_addc_u32 s11, s11, 0
	s_mov_b32 m0, s81
	v_lshl_add_u64 v[238:239], s[10:11], 0, v[162:163]
	ds_read_b128 v[184:187], v199 offset:32768
	ds_read_b128 v[188:191], v199 offset:33792
	ds_read_b128 v[206:209], v199 offset:34816
	ds_read_b128 v[210:213], v199 offset:35840
	ds_read_b128 v[214:217], v199 offset:36864
	ds_read_b128 v[218:221], v199 offset:37888
	ds_read_b128 v[222:225], v199 offset:38912
	ds_read_b128 v[226:229], v199 offset:39936
	global_load_lds_dwordx4 v[238:239], off
	v_lshl_add_u64 v[238:239], s[10:11], 0, v[166:167]
	s_mov_b32 m0, s82
	s_nop 0
	global_load_lds_dwordx4 v[238:239], off
	s_waitcnt vmcnt(8)
	s_waitcnt lgkmcnt(0)
	s_barrier
	s_setprio 1
	s_waitcnt lgkmcnt(0)
	v_mfma_f32_16x16x32_bf16 v[130:133], v[114:117], v[184:187], v[130:133]
	v_mfma_f32_16x16x32_bf16 v[126:129], v[138:141], v[184:187], v[126:129]
	v_mfma_f32_16x16x32_bf16 v[110:113], v[114:117], v[206:209], v[110:113]
	v_mfma_f32_16x16x32_bf16 v[106:109], v[138:141], v[206:209], v[106:109]
	v_mfma_f32_16x16x32_bf16 v[94:97], v[114:117], v[214:217], v[94:97]
	v_mfma_f32_16x16x32_bf16 v[90:93], v[138:141], v[214:217], v[90:93]
	v_mfma_f32_16x16x32_bf16 v[78:81], v[114:117], v[222:225], v[78:81]
	v_mfma_f32_16x16x32_bf16 v[74:77], v[138:141], v[222:225], v[74:77]
	v_mfma_f32_16x16x32_bf16 v[130:133], v[134:137], v[188:191], v[130:133]
	v_mfma_f32_16x16x32_bf16 v[126:129], v[142:145], v[188:191], v[126:129]
	v_mfma_f32_16x16x32_bf16 v[110:113], v[134:137], v[210:213], v[110:113]
	v_mfma_f32_16x16x32_bf16 v[106:109], v[142:145], v[210:213], v[106:109]
	v_mfma_f32_16x16x32_bf16 v[94:97], v[134:137], v[218:221], v[94:97]
	v_mfma_f32_16x16x32_bf16 v[90:93], v[142:145], v[218:221], v[90:93]
	v_mfma_f32_16x16x32_bf16 v[78:81], v[134:137], v[226:229], v[78:81]
	v_mfma_f32_16x16x32_bf16 v[74:77], v[142:145], v[226:229], v[74:77]
	s_setprio 0
	s_setprio 1
	v_mfma_f32_16x16x32_bf16 v[122:125], v[146:149], v[184:187], v[122:125]
	v_mfma_f32_16x16x32_bf16 v[118:121], v[154:157], v[184:187], v[118:121]
	v_mfma_f32_16x16x32_bf16 v[102:105], v[146:149], v[206:209], v[102:105]
	v_mfma_f32_16x16x32_bf16 v[98:101], v[154:157], v[206:209], v[98:101]
	v_mfma_f32_16x16x32_bf16 v[86:89], v[146:149], v[214:217], v[86:89]
	v_mfma_f32_16x16x32_bf16 v[82:85], v[154:157], v[214:217], v[82:85]
	v_mfma_f32_16x16x32_bf16 v[70:73], v[146:149], v[222:225], v[70:73]
	v_mfma_f32_16x16x32_bf16 v[66:69], v[154:157], v[222:225], v[66:69]
	v_mfma_f32_16x16x32_bf16 v[122:125], v[150:153], v[188:191], v[122:125]
	v_mfma_f32_16x16x32_bf16 v[118:121], v[158:161], v[188:191], v[118:121]
	v_mfma_f32_16x16x32_bf16 v[102:105], v[150:153], v[210:213], v[102:105]
	v_mfma_f32_16x16x32_bf16 v[98:101], v[158:161], v[210:213], v[98:101]
	v_mfma_f32_16x16x32_bf16 v[86:89], v[150:153], v[218:221], v[86:89]
	v_mfma_f32_16x16x32_bf16 v[82:85], v[158:161], v[218:221], v[82:85]
	v_mfma_f32_16x16x32_bf16 v[70:73], v[150:153], v[226:229], v[70:73]
	v_mfma_f32_16x16x32_bf16 v[66:69], v[158:161], v[226:229], v[66:69]
	s_setprio 0
	s_barrier
	s_add_i32 s0, s0, s79
	v_lshl_add_u64 v[230:231], v[230:231], 0, s[42:43]
	s_mov_b32 m0, s0
	ds_read_b128 v[184:187], v199 offset:49152
	ds_read_b128 v[188:191], v199 offset:50176
	ds_read_b128 v[206:209], v199 offset:51200
	ds_read_b128 v[210:213], v199 offset:52224
	ds_read_b128 v[214:217], v199 offset:53248
	ds_read_b128 v[218:221], v199 offset:54272
	ds_read_b128 v[222:225], v199 offset:55296
	ds_read_b128 v[226:229], v199 offset:56320
	global_load_lds_dwordx4 v[230:231], off
	s_add_i32 m0, s0, 0x2000
	s_add_u32 s8, s8, 0x40080
	v_lshl_add_u64 v[230:231], v[232:233], 0, s[42:43]
	s_addc_u32 s9, s9, 0
	s_add_i32 s0, s27, s79
	global_load_lds_dwordx4 v[230:231], off
	v_lshl_add_u64 v[230:231], s[8:9], 0, v[164:165]
	s_mov_b32 m0, s0
	s_nop 0
	global_load_lds_dwordx4 v[230:231], off
	v_lshl_add_u64 v[230:231], s[8:9], 0, v[168:169]
	s_add_i32 m0, s0, 0x2000
	s_nop 0
	global_load_lds_dwordx4 v[230:231], off
	v_lshl_add_u64 v[230:231], v[234:235], 0, s[42:43]
	s_mov_b32 m0, s84
	s_nop 0
	global_load_lds_dwordx4 v[230:231], off
	v_lshl_add_u64 v[230:231], v[236:237], 0, s[42:43]
	s_mov_b32 m0, s85
	s_nop 0
	global_load_lds_dwordx4 v[230:231], off
	s_waitcnt vmcnt(8)
	s_waitcnt lgkmcnt(0)
	s_barrier
	s_setprio 1
	s_waitcnt lgkmcnt(0)
	v_mfma_f32_16x16x32_bf16 v[62:65], v[114:117], v[184:187], v[62:65]
	v_mfma_f32_16x16x32_bf16 v[58:61], v[138:141], v[184:187], v[58:61]
	v_mfma_f32_16x16x32_bf16 v[46:49], v[114:117], v[206:209], v[46:49]
	v_mfma_f32_16x16x32_bf16 v[42:45], v[138:141], v[206:209], v[42:45]
	v_mfma_f32_16x16x32_bf16 v[30:33], v[114:117], v[214:217], v[30:33]
	v_mfma_f32_16x16x32_bf16 v[26:29], v[138:141], v[214:217], v[26:29]
	v_mfma_f32_16x16x32_bf16 v[14:17], v[114:117], v[222:225], v[14:17]
	v_mfma_f32_16x16x32_bf16 v[10:13], v[138:141], v[222:225], v[10:13]
	v_mfma_f32_16x16x32_bf16 v[62:65], v[134:137], v[188:191], v[62:65]
	v_mfma_f32_16x16x32_bf16 v[58:61], v[142:145], v[188:191], v[58:61]
	v_mfma_f32_16x16x32_bf16 v[46:49], v[134:137], v[210:213], v[46:49]
	v_mfma_f32_16x16x32_bf16 v[42:45], v[142:145], v[210:213], v[42:45]
	v_mfma_f32_16x16x32_bf16 v[30:33], v[134:137], v[218:221], v[30:33]
	v_mfma_f32_16x16x32_bf16 v[26:29], v[142:145], v[218:221], v[26:29]
	v_mfma_f32_16x16x32_bf16 v[14:17], v[134:137], v[226:229], v[14:17]
	v_mfma_f32_16x16x32_bf16 v[10:13], v[142:145], v[226:229], v[10:13]
	s_setprio 0
	s_setprio 1
	v_mfma_f32_16x16x32_bf16 v[54:57], v[146:149], v[184:187], v[54:57]
	v_mfma_f32_16x16x32_bf16 v[50:53], v[154:157], v[184:187], v[50:53]
	v_mfma_f32_16x16x32_bf16 v[38:41], v[146:149], v[206:209], v[38:41]
	v_mfma_f32_16x16x32_bf16 v[34:37], v[154:157], v[206:209], v[34:37]
	v_mfma_f32_16x16x32_bf16 v[22:25], v[146:149], v[214:217], v[22:25]
	v_mfma_f32_16x16x32_bf16 v[18:21], v[154:157], v[214:217], v[18:21]
	v_mfma_f32_16x16x32_bf16 v[6:9], v[146:149], v[222:225], v[6:9]
	v_mfma_f32_16x16x32_bf16 v[2:5], v[154:157], v[222:225], v[2:5]
	v_mfma_f32_16x16x32_bf16 v[54:57], v[150:153], v[188:191], v[54:57]
	v_mfma_f32_16x16x32_bf16 v[50:53], v[158:161], v[188:191], v[50:53]
	v_mfma_f32_16x16x32_bf16 v[38:41], v[150:153], v[210:213], v[38:41]
	v_mfma_f32_16x16x32_bf16 v[34:37], v[158:161], v[210:213], v[34:37]
	v_mfma_f32_16x16x32_bf16 v[22:25], v[150:153], v[218:221], v[22:25]
	v_mfma_f32_16x16x32_bf16 v[18:21], v[158:161], v[218:221], v[18:21]
	v_mfma_f32_16x16x32_bf16 v[6:9], v[150:153], v[226:229], v[6:9]
	v_mfma_f32_16x16x32_bf16 v[2:5], v[158:161], v[226:229], v[2:5]
	s_setprio 0
	s_barrier
	s_add_i32 s26, s26, 2
	s_add_u32 s6, s6, 0x100
	s_addc_u32 s7, s7, 0
	s_add_u32 s24, s24, 0x100
	s_addc_u32 s25, s25, 0
	s_cmp_gt_u32 s26, 13
	s_cbranch_scc0 .LBB0_368
	s_and_b64 vcc, exec, s[46:47]
	s_cbranch_vccz .LBB0_371

.LBB0_822:
	s_mov_b32 s40, 4
	s_cmp_lt_i32 s40, 1
	s_cbranch_scc1 .LBB0_825
	v_mov_b64_e32 v[2:3], 0
	s_mov_b32 s41, 0
	s_mov_b64 s[44:45], 0
	s_mov_b64 s[38:39], s[12:13]
	v_mov_b64_e32 v[4:5], 0
	v_mov_b64_e32 v[6:7], 0
	v_mov_b64_e32 v[8:9], 0
	v_mov_b64_e32 v[18:19], 0
	v_mov_b64_e32 v[20:21], 0
	v_mov_b64_e32 v[22:23], 0
	v_mov_b64_e32 v[24:25], 0
	v_mov_b64_e32 v[34:35], 0
	v_mov_b64_e32 v[36:37], 0
	v_mov_b64_e32 v[38:39], 0
	v_mov_b64_e32 v[40:41], 0
	v_mov_b64_e32 v[50:51], 0
	v_mov_b64_e32 v[52:53], 0
	v_mov_b64_e32 v[54:55], 0
	v_mov_b64_e32 v[56:57], 0
	v_mov_b64_e32 v[10:11], 0
	v_mov_b64_e32 v[12:13], 0
	v_mov_b64_e32 v[14:15], 0
	v_mov_b64_e32 v[16:17], 0
	v_mov_b64_e32 v[26:27], 0
	v_mov_b64_e32 v[28:29], 0
	v_mov_b64_e32 v[30:31], 0
	v_mov_b64_e32 v[32:33], 0
	v_mov_b64_e32 v[42:43], 0
	v_mov_b64_e32 v[44:45], 0
	v_mov_b64_e32 v[46:47], 0
	v_mov_b64_e32 v[48:49], 0
	v_mov_b64_e32 v[58:59], 0
	v_mov_b64_e32 v[60:61], 0
	v_mov_b64_e32 v[62:63], 0
	v_mov_b64_e32 v[64:65], 0
	v_mov_b64_e32 v[78:79], 0
	v_mov_b64_e32 v[80:81], 0
	v_mov_b64_e32 v[90:91], 0
	v_mov_b64_e32 v[92:93], 0
	v_mov_b64_e32 v[122:123], 0
	v_mov_b64_e32 v[124:125], 0
	v_mov_b64_e32 v[118:119], 0
	v_mov_b64_e32 v[120:121], 0
	v_mov_b64_e32 v[106:107], 0
	v_mov_b64_e32 v[108:109], 0
	v_mov_b64_e32 v[98:99], 0
	v_mov_b64_e32 v[100:101], 0
	v_mov_b64_e32 v[82:83], 0
	v_mov_b64_e32 v[84:85], 0
	v_mov_b64_e32 v[74:75], 0
	v_mov_b64_e32 v[76:77], 0
	v_mov_b64_e32 v[102:103], 0
	v_mov_b64_e32 v[104:105], 0
	v_mov_b64_e32 v[126:127], 0
	v_mov_b64_e32 v[128:129], 0
	v_mov_b64_e32 v[114:115], 0
	v_mov_b64_e32 v[116:117], 0
	v_mov_b64_e32 v[110:111], 0
	v_mov_b64_e32 v[112:113], 0
	v_mov_b64_e32 v[94:95], 0
	v_mov_b64_e32 v[96:97], 0
	v_mov_b64_e32 v[86:87], 0
	v_mov_b64_e32 v[88:89], 0
	v_mov_b64_e32 v[66:67], 0
	v_mov_b64_e32 v[68:69], 0
	v_mov_b64_e32 v[70:71], 0
	v_mov_b64_e32 v[72:73], 0

.LBB0_902:
	s_mov_b64 s[28:29], s[10:11]
	s_mov_b32 s10, s37
	s_mov_b32 s0, s37
	s_add_i32 s37, s47, s1
	s_mov_b64 s[30:31], s[8:9]
	s_and_b64 s[8:9], s[26:27], exec
	s_cselect_b32 s8, s37, s10
	s_cselect_b32 s10, s46, s46
	s_ashr_i32 s11, s10, 31
	s_lshl_b64 s[10:11], s[10:11], 19
	s_add_u32 s10, s2, s10
	s_addc_u32 s11, s3, s11
	s_and_b64 s[34:35], s[26:27], exec
	s_cselect_b32 s1, s11, s29
	s_cselect_b32 s50, s10, s28
	s_ashr_i32 s9, s8, 31
	s_lshl_b64 s[8:9], s[8:9], 19
	s_add_u32 s8, s4, s8
	s_addc_u32 s9, s5, s9
	s_and_b64 s[34:35], s[26:27], exec
	s_cselect_b32 s51, s9, s31
	s_cselect_b32 s52, s8, s30
	s_add_u32 s28, s28, 0x40080
	s_addc_u32 s29, s29, 0
	s_add_u32 s53, s30, 0x100
	v_mov_b64_e32 v[2:3], 0
	s_addc_u32 s54, s31, 0
	s_mov_b32 s55, -2
	s_waitcnt lgkmcnt(0)
	v_mov_b64_e32 v[4:5], 0
	v_mov_b64_e32 v[6:7], 0
	v_mov_b64_e32 v[8:9], 0
	v_mov_b64_e32 v[18:19], 0
	v_mov_b64_e32 v[20:21], 0
	v_mov_b64_e32 v[22:23], 0
	v_mov_b64_e32 v[24:25], 0
	v_mov_b64_e32 v[34:35], 0
	v_mov_b64_e32 v[36:37], 0
	v_mov_b64_e32 v[38:39], 0
	v_mov_b64_e32 v[40:41], 0
	v_mov_b64_e32 v[50:51], 0
	v_mov_b64_e32 v[52:53], 0
	v_mov_b64_e32 v[54:55], 0
	v_mov_b64_e32 v[56:57], 0
	v_mov_b64_e32 v[10:11], 0
	v_mov_b64_e32 v[12:13], 0
	v_mov_b64_e32 v[14:15], 0
	v_mov_b64_e32 v[16:17], 0
	v_mov_b64_e32 v[26:27], 0
	v_mov_b64_e32 v[28:29], 0
	v_mov_b64_e32 v[30:31], 0
	v_mov_b64_e32 v[32:33], 0
	v_mov_b64_e32 v[42:43], 0
	v_mov_b64_e32 v[44:45], 0
	v_mov_b64_e32 v[46:47], 0
	v_mov_b64_e32 v[48:49], 0
	v_mov_b64_e32 v[58:59], 0
	v_mov_b64_e32 v[60:61], 0
	v_mov_b64_e32 v[62:63], 0
	v_mov_b64_e32 v[64:65], 0
	v_mov_b64_e32 v[66:67], 0
	v_mov_b64_e32 v[68:69], 0
	v_mov_b64_e32 v[70:71], 0
	v_mov_b64_e32 v[72:73], 0
	v_mov_b64_e32 v[82:83], 0
	v_mov_b64_e32 v[84:85], 0
	v_mov_b64_e32 v[86:87], 0
	v_mov_b64_e32 v[88:89], 0
	v_mov_b64_e32 v[98:99], 0
	v_mov_b64_e32 v[100:101], 0
	v_mov_b64_e32 v[102:103], 0
	v_mov_b64_e32 v[104:105], 0
	v_mov_b64_e32 v[114:115], 0
	v_mov_b64_e32 v[116:117], 0
	v_mov_b64_e32 v[118:119], 0
	v_mov_b64_e32 v[120:121], 0
	v_mov_b64_e32 v[74:75], 0
	v_mov_b64_e32 v[76:77], 0
	v_mov_b64_e32 v[78:79], 0
	v_mov_b64_e32 v[80:81], 0
	v_mov_b64_e32 v[90:91], 0
	v_mov_b64_e32 v[92:93], 0
	v_mov_b64_e32 v[94:95], 0
	v_mov_b64_e32 v[96:97], 0
	v_mov_b64_e32 v[106:107], 0
	v_mov_b64_e32 v[108:109], 0
	v_mov_b64_e32 v[110:111], 0
	v_mov_b64_e32 v[112:113], 0
	v_mov_b64_e32 v[122:123], 0
	v_mov_b64_e32 v[124:125], 0
	v_mov_b64_e32 v[126:127], 0
	v_mov_b64_e32 v[128:129], 0

.LBB0_990:
	s_ashr_i32 s37, s36, 31
	s_lshl_b64 s[2:3], s[36:37], 19
	s_add_u32 s40, s48, s2
	s_addc_u32 s41, s49, s3
	s_and_b64 s[2:3], s[44:45], exec
	s_cselect_b32 s1, s41, s9
	s_cselect_b32 s2, s40, s8
	s_ashr_i32 s39, s38, 31
	s_lshl_b64 s[4:5], s[38:39], 19
	s_add_u32 s42, s50, s4
	s_addc_u32 s43, s51, s5
	s_and_b64 s[4:5], s[44:45], exec
	s_cselect_b32 s3, s43, s11
	s_cselect_b32 s4, s42, s10
	s_add_u32 s8, s8, 0x40080
	s_addc_u32 s9, s9, 0
	s_add_u32 s5, s10, 0x100
	v_mov_b64_e32 v[2:3], 0
	s_addc_u32 s7, s11, 0
	s_mov_b32 s22, -2
	v_mov_b64_e32 v[4:5], 0
	v_mov_b64_e32 v[6:7], 0
	v_mov_b64_e32 v[8:9], 0
	v_mov_b64_e32 v[18:19], 0
	v_mov_b64_e32 v[20:21], 0
	v_mov_b64_e32 v[22:23], 0
	v_mov_b64_e32 v[24:25], 0
	v_mov_b64_e32 v[34:35], 0
	v_mov_b64_e32 v[36:37], 0
	v_mov_b64_e32 v[38:39], 0
	v_mov_b64_e32 v[40:41], 0
	v_mov_b64_e32 v[50:51], 0
	v_mov_b64_e32 v[52:53], 0
	v_mov_b64_e32 v[58:59], 0
	v_mov_b64_e32 v[60:61], 0
	v_mov_b64_e32 v[10:11], 0
	v_mov_b64_e32 v[12:13], 0
	v_mov_b64_e32 v[14:15], 0
	v_mov_b64_e32 v[16:17], 0
	v_mov_b64_e32 v[26:27], 0
	v_mov_b64_e32 v[28:29], 0
	v_mov_b64_e32 v[30:31], 0
	v_mov_b64_e32 v[32:33], 0
	v_mov_b64_e32 v[42:43], 0
	v_mov_b64_e32 v[44:45], 0
	v_mov_b64_e32 v[46:47], 0
	v_mov_b64_e32 v[48:49], 0
	v_mov_b64_e32 v[54:55], 0
	v_mov_b64_e32 v[56:57], 0
	v_mov_b64_e32 v[62:63], 0
	v_mov_b64_e32 v[64:65], 0
	v_mov_b64_e32 v[74:75], 0
	v_mov_b64_e32 v[76:77], 0
	v_mov_b64_e32 v[78:79], 0
	v_mov_b64_e32 v[80:81], 0
	v_mov_b64_e32 v[94:95], 0
	v_mov_b64_e32 v[96:97], 0
	v_mov_b64_e32 v[98:99], 0
	v_mov_b64_e32 v[100:101], 0
	v_mov_b64_e32 v[114:115], 0
	v_mov_b64_e32 v[116:117], 0
	v_mov_b64_e32 v[118:119], 0
	v_mov_b64_e32 v[120:121], 0
	v_mov_b64_e32 v[130:131], 0
	v_mov_b64_e32 v[132:133], 0
	v_mov_b64_e32 v[138:139], 0
	v_mov_b64_e32 v[140:141], 0
	v_mov_b64_e32 v[82:83], 0
	v_mov_b64_e32 v[84:85], 0
	v_mov_b64_e32 v[90:91], 0
	v_mov_b64_e32 v[92:93], 0
	v_mov_b64_e32 v[102:103], 0
	v_mov_b64_e32 v[104:105], 0
	v_mov_b64_e32 v[110:111], 0
	v_mov_b64_e32 v[112:113], 0
	v_mov_b64_e32 v[122:123], 0
	v_mov_b64_e32 v[124:125], 0
	v_mov_b64_e32 v[126:127], 0
	v_mov_b64_e32 v[128:129], 0
	v_mov_b64_e32 v[134:135], 0
	v_mov_b64_e32 v[136:137], 0
	v_mov_b64_e32 v[142:143], 0
	v_mov_b64_e32 v[144:145], 0
.LBB0_991:
	ds_read_b128 v[66:69], v219
	ds_read_b128 v[70:73], v219 offset:1024
	ds_read_b128 v[86:89], v219 offset:2048
	ds_read_b128 v[106:109], v219 offset:3072
	ds_read_b128 v[146:149], v220
	ds_read_b128 v[150:153], v220 offset:1024
	ds_read_b128 v[154:157], v220 offset:2048
	ds_read_b128 v[158:161], v220 offset:3072
	s_add_u32 s10, s8, 0xfffc0080
	s_addc_u32 s11, s9, -1
	s_cmp_eq_u32 s22, 12
	s_cselect_b32 s45, s1, s11
	s_cselect_b32 s44, s2, s10
	s_cselect_b32 s11, s3, s7
	s_cselect_b32 s10, s4, s5
	v_lshl_add_u64 v[224:225], s[8:9], 0, v[192:193]
	s_add_i32 m0, s54, 0xc000
	ds_read_b128 v[162:165], v221
	ds_read_b128 v[166:169], v221 offset:1024
	ds_read_b128 v[170:173], v221 offset:2048
	ds_read_b128 v[174:177], v221 offset:3072
	ds_read_b128 v[196:199], v221 offset:4096
	ds_read_b128 v[200:203], v221 offset:5120
	ds_read_b128 v[204:207], v221 offset:6144
	ds_read_b128 v[208:211], v221 offset:7168
	global_load_lds_dwordx4 v[224:225], off
	v_lshl_add_u64 v[224:225], s[8:9], 0, v[194:195]
	s_add_i32 m0, s54, 0xe000
	s_nop 0
	global_load_lds_dwordx4 v[224:225], off
	s_waitcnt vmcnt(8)
	s_waitcnt lgkmcnt(0)
	s_barrier
	s_setprio 1
	s_waitcnt lgkmcnt(0)
	v_mfma_f32_16x16x32_bf16 v[142:145], v[66:69], v[162:165], v[142:145]
	v_mfma_f32_16x16x32_bf16 v[134:137], v[86:89], v[162:165], v[134:137]
	v_mfma_f32_16x16x32_bf16 v[126:129], v[66:69], v[170:173], v[126:129]
	v_mfma_f32_16x16x32_bf16 v[122:125], v[86:89], v[170:173], v[122:125]
	v_mfma_f32_16x16x32_bf16 v[110:113], v[66:69], v[196:199], v[110:113]
	v_mfma_f32_16x16x32_bf16 v[102:105], v[86:89], v[196:199], v[102:105]
	v_mfma_f32_16x16x32_bf16 v[90:93], v[66:69], v[204:207], v[90:93]
	v_mfma_f32_16x16x32_bf16 v[82:85], v[86:89], v[204:207], v[82:85]
	v_mfma_f32_16x16x32_bf16 v[142:145], v[70:73], v[166:169], v[142:145]
	v_mfma_f32_16x16x32_bf16 v[134:137], v[106:109], v[166:169], v[134:137]
	v_mfma_f32_16x16x32_bf16 v[126:129], v[70:73], v[174:177], v[126:129]
	v_mfma_f32_16x16x32_bf16 v[122:125], v[106:109], v[174:177], v[122:125]
	v_mfma_f32_16x16x32_bf16 v[110:113], v[70:73], v[200:203], v[110:113]
	v_mfma_f32_16x16x32_bf16 v[102:105], v[106:109], v[200:203], v[102:105]
	v_mfma_f32_16x16x32_bf16 v[90:93], v[70:73], v[208:211], v[90:93]
	v_mfma_f32_16x16x32_bf16 v[82:85], v[106:109], v[208:211], v[82:85]
	s_setprio 0
	s_setprio 1
	v_mfma_f32_16x16x32_bf16 v[138:141], v[146:149], v[162:165], v[138:141]
	v_mfma_f32_16x16x32_bf16 v[130:133], v[154:157], v[162:165], v[130:133]
	v_mfma_f32_16x16x32_bf16 v[118:121], v[146:149], v[170:173], v[118:121]
	v_mfma_f32_16x16x32_bf16 v[114:117], v[154:157], v[170:173], v[114:117]
	v_mfma_f32_16x16x32_bf16 v[98:101], v[146:149], v[196:199], v[98:101]
	v_mfma_f32_16x16x32_bf16 v[94:97], v[154:157], v[196:199], v[94:97]
	v_mfma_f32_16x16x32_bf16 v[78:81], v[146:149], v[204:207], v[78:81]
	v_mfma_f32_16x16x32_bf16 v[74:77], v[154:157], v[204:207], v[74:77]
	v_mfma_f32_16x16x32_bf16 v[138:141], v[150:153], v[166:169], v[138:141]
	v_mfma_f32_16x16x32_bf16 v[130:133], v[158:161], v[166:169], v[130:133]
	v_mfma_f32_16x16x32_bf16 v[118:121], v[150:153], v[174:177], v[118:121]
	v_mfma_f32_16x16x32_bf16 v[114:117], v[158:161], v[174:177], v[114:117]
	v_mfma_f32_16x16x32_bf16 v[98:101], v[150:153], v[200:203], v[98:101]
	v_mfma_f32_16x16x32_bf16 v[94:97], v[158:161], v[200:203], v[94:97]
	v_mfma_f32_16x16x32_bf16 v[78:81], v[150:153], v[208:211], v[78:81]
	v_mfma_f32_16x16x32_bf16 v[74:77], v[158:161], v[208:211], v[74:77]
	s_setprio 0
	s_barrier
	s_add_i32 s37, s62, s53
	v_lshl_add_u64 v[224:225], s[10:11], 0, v[184:185]
	s_mov_b32 m0, s37
	ds_read_b128 v[162:165], v221 offset:16384
	ds_read_b128 v[166:169], v221 offset:17408
	ds_read_b128 v[170:173], v221 offset:18432
	ds_read_b128 v[174:177], v221 offset:19456
	ds_read_b128 v[196:199], v221 offset:20480
	ds_read_b128 v[200:203], v221 offset:21504
	ds_read_b128 v[204:207], v221 offset:22528
	ds_read_b128 v[208:211], v221 offset:23552
	global_load_lds_dwordx4 v[224:225], off
	s_add_i32 m0, s37, 0x2000
	s_add_u32 s46, s10, 0x40000
	v_lshl_add_u64 v[226:227], s[10:11], 0, v[188:189]
	s_addc_u32 s47, s11, 0
	s_add_i32 s37, s63, s53
	global_load_lds_dwordx4 v[226:227], off
	v_lshl_add_u64 v[228:229], s[46:47], 0, v[184:185]
	s_mov_b32 m0, s37
	v_lshl_add_u64 v[230:231], s[44:45], 0, v[186:187]
	global_load_lds_dwordx4 v[228:229], off
	v_lshl_add_u64 v[228:229], s[46:47], 0, v[188:189]
	s_add_i32 m0, s37, 0x2000
	s_nop 0
	global_load_lds_dwordx4 v[228:229], off
	v_lshl_add_u64 v[228:229], s[44:45], 0, v[182:183]
	s_mov_b32 m0, s54
	s_nop 0
	global_load_lds_dwordx4 v[228:229], off
	s_mov_b32 m0, s55
	s_nop 0
	global_load_lds_dwordx4 v[230:231], off
	s_waitcnt vmcnt(8)
	s_waitcnt lgkmcnt(0)
	s_barrier
	s_setprio 1
	s_waitcnt lgkmcnt(0)
	v_mfma_f32_16x16x32_bf16 v[62:65], v[66:69], v[162:165], v[62:65]
	v_mfma_f32_16x16x32_bf16 v[54:57], v[86:89], v[162:165], v[54:57]
	v_mfma_f32_16x16x32_bf16 v[46:49], v[66:69], v[170:173], v[46:49]
	v_mfma_f32_16x16x32_bf16 v[42:45], v[86:89], v[170:173], v[42:45]
	v_mfma_f32_16x16x32_bf16 v[30:33], v[66:69], v[196:199], v[30:33]
	v_mfma_f32_16x16x32_bf16 v[26:29], v[86:89], v[196:199], v[26:29]
	v_mfma_f32_16x16x32_bf16 v[14:17], v[66:69], v[204:207], v[14:17]
	v_mfma_f32_16x16x32_bf16 v[10:13], v[86:89], v[204:207], v[10:13]
	v_mfma_f32_16x16x32_bf16 v[62:65], v[70:73], v[166:169], v[62:65]
	v_mfma_f32_16x16x32_bf16 v[54:57], v[106:109], v[166:169], v[54:57]
	v_mfma_f32_16x16x32_bf16 v[46:49], v[70:73], v[174:177], v[46:49]
	v_mfma_f32_16x16x32_bf16 v[42:45], v[106:109], v[174:177], v[42:45]
	v_mfma_f32_16x16x32_bf16 v[30:33], v[70:73], v[200:203], v[30:33]
	v_mfma_f32_16x16x32_bf16 v[26:29], v[106:109], v[200:203], v[26:29]
	v_mfma_f32_16x16x32_bf16 v[14:17], v[70:73], v[208:211], v[14:17]
	v_mfma_f32_16x16x32_bf16 v[10:13], v[106:109], v[208:211], v[10:13]
	s_setprio 0
	s_setprio 1
	v_mfma_f32_16x16x32_bf16 v[58:61], v[146:149], v[162:165], v[58:61]
	v_mfma_f32_16x16x32_bf16 v[50:53], v[154:157], v[162:165], v[50:53]
	v_mfma_f32_16x16x32_bf16 v[38:41], v[146:149], v[170:173], v[38:41]
	v_mfma_f32_16x16x32_bf16 v[34:37], v[154:157], v[170:173], v[34:37]
	v_mfma_f32_16x16x32_bf16 v[22:25], v[146:149], v[196:199], v[22:25]
	v_mfma_f32_16x16x32_bf16 v[18:21], v[154:157], v[196:199], v[18:21]
	v_mfma_f32_16x16x32_bf16 v[6:9], v[146:149], v[204:207], v[6:9]
	v_mfma_f32_16x16x32_bf16 v[2:5], v[154:157], v[204:207], v[2:5]
	v_mfma_f32_16x16x32_bf16 v[58:61], v[150:153], v[166:169], v[58:61]
	v_mfma_f32_16x16x32_bf16 v[50:53], v[158:161], v[166:169], v[50:53]
	v_mfma_f32_16x16x32_bf16 v[38:41], v[150:153], v[174:177], v[38:41]
	v_mfma_f32_16x16x32_bf16 v[34:37], v[158:161], v[174:177], v[34:37]
	v_mfma_f32_16x16x32_bf16 v[22:25], v[150:153], v[200:203], v[22:25]
	v_mfma_f32_16x16x32_bf16 v[18:21], v[158:161], v[200:203], v[18:21]
	v_mfma_f32_16x16x32_bf16 v[6:9], v[150:153], v[208:211], v[6:9]
	v_mfma_f32_16x16x32_bf16 v[2:5], v[158:161], v[208:211], v[2:5]
	s_setprio 0
	s_barrier
	s_add_i32 s37, 0, 0x18000
	s_add_i32 s39, 0, 0x1c000
	v_add_u32_e32 v106, s37, v213
	v_add_u32_e32 v158, s39, v213
	ds_read_b128 v[66:69], v106
	ds_read_b128 v[70:73], v106 offset:1024
	ds_read_b128 v[86:89], v106 offset:2048
	ds_read_b128 v[106:109], v106 offset:3072
	ds_read_b128 v[146:149], v158
	ds_read_b128 v[150:153], v158 offset:1024
	ds_read_b128 v[154:157], v158 offset:2048
	ds_read_b128 v[158:161], v158 offset:3072
	s_add_u32 s44, s44, 0x40000
	s_addc_u32 s45, s45, 0
	s_mov_b32 m0, s56
	v_lshl_add_u64 v[232:233], s[44:45], 0, v[182:183]
	ds_read_b128 v[162:165], v221 offset:32768
	ds_read_b128 v[166:169], v221 offset:33792
	ds_read_b128 v[170:173], v221 offset:34816
	ds_read_b128 v[174:177], v221 offset:35840
	ds_read_b128 v[196:199], v221 offset:36864
	ds_read_b128 v[200:203], v221 offset:37888
	ds_read_b128 v[204:207], v221 offset:38912
	ds_read_b128 v[208:211], v221 offset:39936
	global_load_lds_dwordx4 v[232:233], off
	v_lshl_add_u64 v[232:233], s[44:45], 0, v[186:187]
	s_mov_b32 m0, s57
	s_nop 0
	global_load_lds_dwordx4 v[232:233], off
	s_waitcnt vmcnt(8)
	s_waitcnt lgkmcnt(0)
	s_barrier
	s_setprio 1
	s_waitcnt lgkmcnt(0)
	v_mfma_f32_16x16x32_bf16 v[142:145], v[66:69], v[162:165], v[142:145]
	v_mfma_f32_16x16x32_bf16 v[134:137], v[86:89], v[162:165], v[134:137]
	v_mfma_f32_16x16x32_bf16 v[126:129], v[66:69], v[170:173], v[126:129]
	v_mfma_f32_16x16x32_bf16 v[122:125], v[86:89], v[170:173], v[122:125]
	v_mfma_f32_16x16x32_bf16 v[110:113], v[66:69], v[196:199], v[110:113]
	v_mfma_f32_16x16x32_bf16 v[102:105], v[86:89], v[196:199], v[102:105]
	v_mfma_f32_16x16x32_bf16 v[90:93], v[66:69], v[204:207], v[90:93]
	v_mfma_f32_16x16x32_bf16 v[82:85], v[86:89], v[204:207], v[82:85]
	v_mfma_f32_16x16x32_bf16 v[142:145], v[70:73], v[166:169], v[142:145]
	v_mfma_f32_16x16x32_bf16 v[134:137], v[106:109], v[166:169], v[134:137]
	v_mfma_f32_16x16x32_bf16 v[126:129], v[70:73], v[174:177], v[126:129]
	v_mfma_f32_16x16x32_bf16 v[122:125], v[106:109], v[174:177], v[122:125]
	v_mfma_f32_16x16x32_bf16 v[110:113], v[70:73], v[200:203], v[110:113]
	v_mfma_f32_16x16x32_bf16 v[102:105], v[106:109], v[200:203], v[102:105]
	v_mfma_f32_16x16x32_bf16 v[90:93], v[70:73], v[208:211], v[90:93]
	v_mfma_f32_16x16x32_bf16 v[82:85], v[106:109], v[208:211], v[82:85]
	s_setprio 0
	s_setprio 1
	v_mfma_f32_16x16x32_bf16 v[138:141], v[146:149], v[162:165], v[138:141]
	v_mfma_f32_16x16x32_bf16 v[130:133], v[154:157], v[162:165], v[130:133]
	v_mfma_f32_16x16x32_bf16 v[118:121], v[146:149], v[170:173], v[118:121]
	v_mfma_f32_16x16x32_bf16 v[114:117], v[154:157], v[170:173], v[114:117]
	v_mfma_f32_16x16x32_bf16 v[98:101], v[146:149], v[196:199], v[98:101]
	v_mfma_f32_16x16x32_bf16 v[94:97], v[154:157], v[196:199], v[94:97]
	v_mfma_f32_16x16x32_bf16 v[78:81], v[146:149], v[204:207], v[78:81]
	v_mfma_f32_16x16x32_bf16 v[74:77], v[154:157], v[204:207], v[74:77]
	v_mfma_f32_16x16x32_bf16 v[138:141], v[150:153], v[166:169], v[138:141]
	v_mfma_f32_16x16x32_bf16 v[130:133], v[158:161], v[166:169], v[130:133]
	v_mfma_f32_16x16x32_bf16 v[118:121], v[150:153], v[174:177], v[118:121]
	v_mfma_f32_16x16x32_bf16 v[114:117], v[158:161], v[174:177], v[114:117]
	v_mfma_f32_16x16x32_bf16 v[98:101], v[150:153], v[200:203], v[98:101]
	v_mfma_f32_16x16x32_bf16 v[94:97], v[158:161], v[200:203], v[94:97]
	v_mfma_f32_16x16x32_bf16 v[78:81], v[150:153], v[208:211], v[78:81]
	v_mfma_f32_16x16x32_bf16 v[74:77], v[158:161], v[208:211], v[74:77]
	s_setprio 0
	s_barrier
	s_add_i32 s37, s37, s53
	v_lshl_add_u64 v[224:225], v[224:225], 0, s[28:29]
	s_mov_b32 m0, s37
	ds_read_b128 v[162:165], v221 offset:49152
	ds_read_b128 v[166:169], v221 offset:50176
	ds_read_b128 v[170:173], v221 offset:51200
	ds_read_b128 v[174:177], v221 offset:52224
	ds_read_b128 v[196:199], v221 offset:53248
	ds_read_b128 v[200:203], v221 offset:54272
	ds_read_b128 v[204:207], v221 offset:55296
	ds_read_b128 v[208:211], v221 offset:56320
	global_load_lds_dwordx4 v[224:225], off
	s_add_i32 m0, s37, 0x2000
	s_add_u32 s10, s10, 0x40080
	v_lshl_add_u64 v[224:225], v[226:227], 0, s[28:29]
	s_addc_u32 s11, s11, 0
	s_add_i32 s37, s39, s53
	global_load_lds_dwordx4 v[224:225], off
	v_lshl_add_u64 v[224:225], s[10:11], 0, v[184:185]
	s_mov_b32 m0, s37
	s_nop 0
	global_load_lds_dwordx4 v[224:225], off
	v_lshl_add_u64 v[224:225], s[10:11], 0, v[188:189]
	s_add_i32 m0, s37, 0x2000
	s_nop 0
	global_load_lds_dwordx4 v[224:225], off
	v_lshl_add_u64 v[224:225], v[228:229], 0, s[28:29]
	s_mov_b32 m0, s60
	s_nop 0
	global_load_lds_dwordx4 v[224:225], off
	v_lshl_add_u64 v[224:225], v[230:231], 0, s[28:29]
	s_mov_b32 m0, s61
	s_nop 0
	global_load_lds_dwordx4 v[224:225], off
	s_waitcnt vmcnt(8)
	s_waitcnt lgkmcnt(0)
	s_barrier
	s_setprio 1
	s_waitcnt lgkmcnt(0)
	v_mfma_f32_16x16x32_bf16 v[62:65], v[66:69], v[162:165], v[62:65]
	v_mfma_f32_16x16x32_bf16 v[54:57], v[86:89], v[162:165], v[54:57]
	v_mfma_f32_16x16x32_bf16 v[46:49], v[66:69], v[170:173], v[46:49]
	v_mfma_f32_16x16x32_bf16 v[42:45], v[86:89], v[170:173], v[42:45]
	v_mfma_f32_16x16x32_bf16 v[30:33], v[66:69], v[196:199], v[30:33]
	v_mfma_f32_16x16x32_bf16 v[26:29], v[86:89], v[196:199], v[26:29]
	v_mfma_f32_16x16x32_bf16 v[14:17], v[66:69], v[204:207], v[14:17]
	v_mfma_f32_16x16x32_bf16 v[10:13], v[86:89], v[204:207], v[10:13]
	v_mfma_f32_16x16x32_bf16 v[62:65], v[70:73], v[166:169], v[62:65]
	v_mfma_f32_16x16x32_bf16 v[54:57], v[106:109], v[166:169], v[54:57]
	v_mfma_f32_16x16x32_bf16 v[46:49], v[70:73], v[174:177], v[46:49]
	v_mfma_f32_16x16x32_bf16 v[42:45], v[106:109], v[174:177], v[42:45]
	v_mfma_f32_16x16x32_bf16 v[30:33], v[70:73], v[200:203], v[30:33]
	v_mfma_f32_16x16x32_bf16 v[26:29], v[106:109], v[200:203], v[26:29]
	v_mfma_f32_16x16x32_bf16 v[14:17], v[70:73], v[208:211], v[14:17]
	v_mfma_f32_16x16x32_bf16 v[10:13], v[106:109], v[208:211], v[10:13]
	s_setprio 0
	s_setprio 1
	v_mfma_f32_16x16x32_bf16 v[58:61], v[146:149], v[162:165], v[58:61]
	v_mfma_f32_16x16x32_bf16 v[50:53], v[154:157], v[162:165], v[50:53]
	v_mfma_f32_16x16x32_bf16 v[38:41], v[146:149], v[170:173], v[38:41]
	v_mfma_f32_16x16x32_bf16 v[34:37], v[154:157], v[170:173], v[34:37]
	v_mfma_f32_16x16x32_bf16 v[22:25], v[146:149], v[196:199], v[22:25]
	v_mfma_f32_16x16x32_bf16 v[18:21], v[154:157], v[196:199], v[18:21]
	v_mfma_f32_16x16x32_bf16 v[6:9], v[146:149], v[204:207], v[6:9]
	v_mfma_f32_16x16x32_bf16 v[2:5], v[154:157], v[204:207], v[2:5]
	v_mfma_f32_16x16x32_bf16 v[58:61], v[150:153], v[166:169], v[58:61]
	v_mfma_f32_16x16x32_bf16 v[50:53], v[158:161], v[166:169], v[50:53]
	v_mfma_f32_16x16x32_bf16 v[38:41], v[150:153], v[174:177], v[38:41]
	v_mfma_f32_16x16x32_bf16 v[34:37], v[158:161], v[174:177], v[34:37]
	v_mfma_f32_16x16x32_bf16 v[22:25], v[150:153], v[200:203], v[22:25]
	v_mfma_f32_16x16x32_bf16 v[18:21], v[158:161], v[200:203], v[18:21]
	v_mfma_f32_16x16x32_bf16 v[6:9], v[150:153], v[208:211], v[6:9]
	v_mfma_f32_16x16x32_bf16 v[2:5], v[158:161], v[208:211], v[2:5]
	s_setprio 0
	s_barrier
	s_add_i32 s22, s22, 2
	s_add_u32 s8, s8, 0x100
	s_addc_u32 s9, s9, 0
	s_add_u32 s5, s5, 0x100
	s_addc_u32 s7, s7, 0
	s_cmp_gt_u32 s22, 13
	s_cbranch_scc0 .LBB0_991
	s_and_b64 vcc, exec, s[30:31]
	s_cbranch_vccz .LBB0_994

.LBB0_1107:
	s_and_b64 s[20:21], s[26:27], exec
	s_cselect_b32 s21, s35, s23
	s_cselect_b32 s20, s34, s22
	s_add_u32 s22, s22, 0xb0080
	s_addc_u32 s23, s23, 0
	s_add_u32 s49, s24, 0x100
	v_mov_b64_e32 v[2:3], 0
	s_addc_u32 s50, s25, 0
	s_mov_b32 s51, -2
	v_mov_b64_e32 v[4:5], 0
	v_mov_b64_e32 v[6:7], 0
	v_mov_b64_e32 v[8:9], 0
	v_mov_b64_e32 v[14:15], 0
	v_mov_b64_e32 v[16:17], 0
	v_mov_b64_e32 v[22:23], 0
	v_mov_b64_e32 v[24:25], 0
	v_mov_b64_e32 v[30:31], 0
	v_mov_b64_e32 v[32:33], 0
	v_mov_b64_e32 v[38:39], 0
	v_mov_b64_e32 v[40:41], 0
	v_mov_b64_e32 v[50:51], 0
	v_mov_b64_e32 v[52:53], 0
	v_mov_b64_e32 v[54:55], 0
	v_mov_b64_e32 v[56:57], 0
	v_mov_b64_e32 v[10:11], 0
	v_mov_b64_e32 v[12:13], 0
	v_mov_b64_e32 v[18:19], 0
	v_mov_b64_e32 v[20:21], 0
	v_mov_b64_e32 v[26:27], 0
	v_mov_b64_e32 v[28:29], 0
	v_mov_b64_e32 v[34:35], 0
	v_mov_b64_e32 v[36:37], 0
	v_mov_b64_e32 v[42:43], 0
	v_mov_b64_e32 v[44:45], 0
	v_mov_b64_e32 v[46:47], 0
	v_mov_b64_e32 v[48:49], 0
	v_mov_b64_e32 v[58:59], 0
	v_mov_b64_e32 v[60:61], 0
	v_mov_b64_e32 v[62:63], 0
	v_mov_b64_e32 v[64:65], 0
	v_mov_b64_e32 v[66:67], 0
	v_mov_b64_e32 v[68:69], 0
	v_mov_b64_e32 v[70:71], 0
	v_mov_b64_e32 v[72:73], 0
	v_mov_b64_e32 v[82:83], 0
	v_mov_b64_e32 v[84:85], 0
	v_mov_b64_e32 v[86:87], 0
	v_mov_b64_e32 v[88:89], 0
	v_mov_b64_e32 v[98:99], 0
	v_mov_b64_e32 v[100:101], 0
	v_mov_b64_e32 v[102:103], 0
	v_mov_b64_e32 v[104:105], 0
	v_mov_b64_e32 v[114:115], 0
	v_mov_b64_e32 v[116:117], 0
	v_mov_b64_e32 v[118:119], 0
	v_mov_b64_e32 v[120:121], 0
	v_mov_b64_e32 v[74:75], 0
	v_mov_b64_e32 v[76:77], 0
	v_mov_b64_e32 v[78:79], 0
	v_mov_b64_e32 v[80:81], 0
	v_mov_b64_e32 v[90:91], 0
	v_mov_b64_e32 v[92:93], 0
	v_mov_b64_e32 v[94:95], 0
	v_mov_b64_e32 v[96:97], 0
	v_mov_b64_e32 v[106:107], 0
	v_mov_b64_e32 v[108:109], 0
	v_mov_b64_e32 v[110:111], 0
	v_mov_b64_e32 v[112:113], 0
	v_mov_b64_e32 v[122:123], 0
	v_mov_b64_e32 v[124:125], 0
	v_mov_b64_e32 v[126:127], 0
	v_mov_b64_e32 v[128:129], 0
